# static seeding of phase work queues: first task = blockIdx (no atomic storm at phase start), later fetches offset by grid size (phases B-G, F table loop)
# speedup vs baseline: 1.0152x; 1.0152x over previous
.LBB0_1:
	s_load_dwordx16 s[36:51], s[0:1], 0x0
	s_load_dwordx16 s[52:67], s[0:1], 0x40
	s_load_dwordx16 s[68:83], s[0:1], 0x80
	s_load_dwordx4 s[84:87], s[0:1], 0xe0
	s_load_dwordx8 s[4:11], s[0:1], 0xc0
	s_mov_b32 s29, s2
	v_cmp_eq_u32_e64 s[12:13], 0, v0
	s_mov_b32 s89, 0
	v_mbcnt_lo_u32_b32 v1, -1, 0
	s_waitcnt lgkmcnt(0)
	v_writelane_b32 v253, s4, 4
	v_mbcnt_hi_u32_b32 v198, -1, v1
	v_and_b32_e32 v1, 64, v198
	v_writelane_b32 v253, s5, 5
	v_writelane_b32 v253, s6, 6
	v_writelane_b32 v253, s7, 7
	v_writelane_b32 v253, s8, 8
	v_writelane_b32 v253, s9, 9
	v_writelane_b32 v253, s10, 10
	v_writelane_b32 v253, s11, 11
	s_load_dwordx4 s[4:7], s[0:1], 0xf0
	s_add_u32 s8, s86, 0x400000
	s_addc_u32 s9, s87, 0
	s_cmp_lg_u64 s[64:65], 0
	s_cselect_b64 s[34:35], -1, 0
	s_waitcnt lgkmcnt(0)
	s_cmp_lg_u32 s6, 0
	s_cselect_b64 s[2:3], -1, 0
	v_writelane_b32 v253, s2, 12
	s_mov_b64 s[92:93], 0x100
	v_mov_b32_e32 v131, 0
	v_writelane_b32 v253, s3, 13
	s_and_b32 s2, s29, 15
	s_add_u32 s0, s0, 0x100
	s_addc_u32 s1, s1, 0
	v_writelane_b32 v253, s0, 14
	v_mov_b32_e32 v161, 0x12000
	v_mov_b32_e32 v132, 0x358637bd
	v_writelane_b32 v253, s1, 15
	s_xor_b32 s0, s2, 15
	v_writelane_b32 v253, s0, 16
	s_lshl_b32 s0, s2, 7
	s_add_u32 s0, s8, s0
	v_writelane_b32 v253, s8, 17
	s_addc_u32 s1, s9, 0
	s_mov_b32 s96, 0x3fb8aa3b
	v_writelane_b32 v253, s9, 18
	v_writelane_b32 v253, s0, 19
	s_mov_b32 s97, 0xc2ce8ed0
	s_mov_b32 s26, 0x42b17218
	v_writelane_b32 v253, s1, 20
	s_add_u32 s0, s86, 0x400880
	s_addc_u32 s1, s87, 0
	v_writelane_b32 v253, s0, 21
	s_mov_b32 s33, 0x7f800000
	v_mov_b32_e32 v167, 0x3c0881c4
	v_writelane_b32 v253, s1, 22
	s_add_u32 s0, s86, 0x400900
	v_writelane_b32 v253, s0, 23
	s_addc_u32 s0, s87, 0
	v_writelane_b32 v253, s0, 24
	s_add_u32 s0, s86, 0x415000
	s_addc_u32 s1, s87, 0
	s_add_u32 s94, s86, 0xacb1100
	v_writelane_b32 v253, s0, 25
	s_addc_u32 s95, s87, 0
	v_mov_b32_e32 v173, 0xbab64f3b
	v_writelane_b32 v253, s1, 26
	s_add_u32 s0, s86, 0x8f1100
	v_writelane_b32 v253, s0, 27
	s_addc_u32 s0, s87, 0
	v_writelane_b32 v253, s0, 28
	s_add_u32 s0, s86, 0x9b71100
	v_writelane_b32 v253, s0, 29
	s_addc_u32 s0, s87, 0
	v_writelane_b32 v253, s0, 30
	s_add_u32 s0, s86, 0x9671100
	s_addc_u32 s1, s87, 0
	v_writelane_b32 v253, s0, 31
	v_mov_b32_e32 v135, 1.0
	v_mov_b32_e32 v179, 0xbf1f24be
	v_writelane_b32 v253, s1, 32
	s_add_u32 s0, s86, 0x95f1100
	s_addc_u32 s1, s87, 0
	v_writelane_b32 v253, s0, 33
	v_mov_b32_e32 v196, 0x3e642e9d
	s_mov_b32 s25, 0x41a00000
	v_writelane_b32 v253, s1, 34
	s_add_u32 s0, s86, 0x91f1100
	s_addc_u32 s1, s87, 0
	v_writelane_b32 v253, s0, 35
	s_mov_b32 s24, 0x3f2aaaab
	v_mov_b32_e32 v197, 0x3ecc95a3
	v_writelane_b32 v253, s1, 36
	s_add_u32 s0, s86, 0xa371100
	s_addc_u32 s1, s87, 0
	v_writelane_b32 v253, s0, 37
	s_mov_b32 s23, 0x3f317218
	s_mov_b32 s22, 0x33800000
	v_writelane_b32 v253, s1, 38
	s_add_u32 s0, s86, 0x8d5000
	s_addc_u32 s1, s87, 0
	v_writelane_b32 v253, s0, 39
	v_add_u32_e32 v200, 64, v1
	v_xor_b32_e32 v201, 32, v198
	v_writelane_b32 v253, s1, 40
	s_add_u32 s0, s86, 0x8e5100
	s_addc_u32 s1, s87, 0
	v_writelane_b32 v253, s0, 41
	v_xor_b32_e32 v202, 16, v198
	v_xor_b32_e32 v203, 8, v198
	v_writelane_b32 v253, s1, 42
	s_add_u32 s0, s86, 0x8e9100
	s_addc_u32 s1, s87, 0
	v_writelane_b32 v253, s0, 43
	v_xor_b32_e32 v204, 4, v198
	v_xor_b32_e32 v205, 2, v198
	v_writelane_b32 v253, s1, 44
	s_add_u32 s0, s86, 0x9771100
	v_writelane_b32 v253, s0, 45
	s_addc_u32 s0, s87, 0
	v_writelane_b32 v253, s0, 46
	s_add_u32 s0, s86, 0x401000
	v_writelane_b32 v253, s0, 47
	s_addc_u32 s0, s87, 0
	v_writelane_b32 v253, s0, 48
	s_add_u32 s0, s86, 0x9f1100
	s_addc_u32 s1, s87, 0
	v_writelane_b32 v253, s0, 49
	v_xor_b32_e32 v206, 1, v198
	v_mov_b32_e32 v208, 0x7f800000
	v_writelane_b32 v253, s1, 50
	s_add_u32 s0, s86, 0x671000
	s_addc_u32 s1, s87, 0
	v_writelane_b32 v253, s0, 51
	v_not_b32_e32 v209, 63
	v_not_b32_e32 v210, 31
	v_writelane_b32 v253, s1, 52
	s_add_u32 s0, s86, 0x4df1100
	s_addc_u32 s1, s87, 0
	v_writelane_b32 v253, s0, 53
	v_mov_b32_e32 v211, 0x7fc00000
	v_mov_b32_e32 v207, 0xfffff000
	v_writelane_b32 v253, s1, 54
	s_add_u32 s0, s86, 0x781000
	s_addc_u32 s1, s87, 0
	v_writelane_b32 v253, s0, 55
	v_mov_b32_e32 v216, 0xfc0
	v_mov_b32_e32 v252, 0x1800
	v_writelane_b32 v253, s1, 56
	s_add_u32 s0, s86, 0x2bf1100
	s_addc_u32 s1, s87, 0
	v_writelane_b32 v253, s0, 57
	v_mov_b32_e32 v136, 0x3f317218
	v_mov_b32_e32 v217, 0xffc00000
	v_writelane_b32 v253, s1, 58
	s_add_u32 s0, s86, 0x3cf1100
	s_addc_u32 s1, s87, 0
	v_writelane_b32 v253, s0, 59
	s_mov_b32 s14, s4
	s_nop 0
	v_writelane_b32 v253, s1, 60
	s_add_u32 s0, s86, 0xc571100
	v_writelane_b32 v253, s0, 61
	s_addc_u32 s0, s87, 0
	v_writelane_b32 v253, s0, 62
	s_add_u32 s0, s86, 0xcdf1100
	v_writelane_b32 v253, s0, 63
	s_addc_u32 s0, s87, 0
	s_add_u32 s30, s86, 0x451000
	s_addc_u32 s31, s87, 0
	v_writelane_b32 v254, s0, 0
	s_add_u32 s0, s86, 0xd671100
	s_addc_u32 s1, s87, 0
	v_writelane_b32 v254, s0, 1
	s_nop 1
	v_writelane_b32 v254, s1, 2
	s_add_u32 s0, s86, 0x891000
	s_addc_u32 s1, s87, 0
	v_writelane_b32 v254, s0, 3
	s_nop 1
	v_writelane_b32 v254, s1, 4
	s_add_u32 s0, s86, 0x6ff1100
	s_addc_u32 s1, s87, 0
	v_writelane_b32 v254, s0, 5
	s_nop 1
	v_writelane_b32 v254, s1, 6
	s_add_u32 s0, s86, 0x5ef1100
	s_addc_u32 s1, s87, 0
	v_writelane_b32 v254, s0, 7
	s_nop 1
	v_writelane_b32 v254, s1, 8
	s_add_u32 s0, s86, 0x80f1100
	s_addc_u32 s1, s87, 0
	v_writelane_b32 v254, s0, 9
	s_nop 1
	v_writelane_b32 v254, s1, 10
	s_add_u32 s0, s86, 0x8dd000
	v_writelane_b32 v254, s0, 11
	s_addc_u32 s0, s87, 0
	v_writelane_b32 v254, s0, 12
	s_add_u32 s0, s86, 0x8dd040
	v_writelane_b32 v254, s0, 13
	s_addc_u32 s0, s87, 0
	v_writelane_b32 v254, s0, 14
	s_add_u32 s0, s86, 0x9771300
	v_writelane_b32 v254, s0, 15
	s_addc_u32 s0, s87, 0
	v_writelane_b32 v254, s0, 16
	s_add_u32 s0, s54, 16
	v_writelane_b32 v254, s0, 17
	s_addc_u32 s0, s55, 0
	v_writelane_b32 v254, s0, 18
	s_mov_b32 s0, 0
	v_writelane_b32 v254, s0, 19
	v_writelane_b32 v254, s29, 20
	v_writelane_b32 v254, s52, 21
	s_nop 1
	v_writelane_b32 v254, s53, 22
	v_writelane_b32 v254, s54, 23
	v_writelane_b32 v254, s55, 24
	v_writelane_b32 v254, s56, 25
	v_writelane_b32 v254, s57, 26
	v_writelane_b32 v254, s58, 27
	v_writelane_b32 v254, s59, 28
	v_writelane_b32 v254, s60, 29
	v_writelane_b32 v254, s61, 30
	v_writelane_b32 v254, s62, 31
	v_writelane_b32 v254, s63, 32
	v_writelane_b32 v254, s64, 33
	v_writelane_b32 v254, s65, 34
	v_writelane_b32 v254, s66, 35
	v_writelane_b32 v254, s67, 36
	v_writelane_b32 v254, s12, 37
	s_nop 1
	v_writelane_b32 v254, s13, 38
	v_writelane_b32 v254, s34, 39
	s_nop 1
	v_writelane_b32 v254, s35, 40
	v_writelane_b32 v254, s94, 41
	s_nop 1
	v_writelane_b32 v254, s95, 42
	v_readlane_b32 s0, v253, 14
	v_readlane_b32 s1, v253, 15
	s_load_dword s0, s[0:1], 0x0
	s_waitcnt lgkmcnt(0)
	s_nop 1
	v_writelane_b32 v255, s0, 13
	s_branch .LBB0_5

.LBB0_9:
	v_readlane_b32 s0, v254, 45
	v_readlane_b32 s1, v254, 46
	s_mov_b32 s4, s0
	s_add_i32 s0, s0, -2
	s_mul_hi_i32 s1, s0, 0x92492493
	s_add_i32 s1, s1, s0
	s_lshr_b32 s2, s1, 31
	s_ashr_i32 s1, s1, 2
	s_add_i32 s1, s1, s2
	v_writelane_b32 v254, s1, 51
	s_mul_i32 s1, s1, 7
	s_sub_i32 s18, s0, s1
	s_sub_i32 s0, s4, 23
	s_cmp_lt_u32 s0, 7
	s_cselect_b64 s[2:3], -1, 0
	v_writelane_b32 v254, s2, 47
	s_cmp_gt_u32 s0, 6
	s_cselect_b64 s[0:1], -1, 0
	v_writelane_b32 v254, s3, 48
	v_writelane_b32 v254, s0, 52
	s_mov_b64 s[2:3], 0
	s_cmp_lt_i32 s18, 3
	v_writelane_b32 v254, s1, 53
	v_writelane_b32 v254, s2, 54
	s_mov_b64 s[0:1], -1
	s_nop 0
	v_writelane_b32 v254, s3, 55
	v_writelane_b32 v254, s18, 49
	s_cbranch_scc1 .LBB0_399
	s_cmp_gt_i32 s18, 3
	s_cbranch_scc0 .LBB0_115
	s_cmp_gt_i32 s18, 4
	s_cbranch_scc0 .LBB0_116
	s_cmp_eq_u32 s18, 5
	s_cbranch_scc0 .LBB0_165
	s_barrier
	s_and_saveexec_b64 s[0:1], s[12:13]
	s_cbranch_execz .LBB0_17
	s_mov_b64 s[4:5], exec
	v_mbcnt_lo_u32_b32 v1, s4, 0
	v_mbcnt_hi_u32_b32 v1, s5, v1
	v_cmp_eq_u32_e32 vcc, 0, v1
	s_and_saveexec_b64 s[2:3], vcc
	s_cbranch_execz .LBB0_16
	s_bcnt1_i32_b64 s4, s[4:5]
	s_waitcnt vmcnt(0)
	v_mov_b32_e32 v2, s4
	v_readlane_b32 s4, v254, 43
	v_readlane_b32 s5, v254, 44
	s_nop 4
	v_readlane_b32 s4, v254, 20
	s_nop 1
	v_mov_b32_e32 v2, s4

.LBB0_72:
	s_or_b64 exec, exec, s[0:1]
	s_waitcnt lgkmcnt(0)
	s_barrier
	ds_read_b32 v1, v161
	s_waitcnt lgkmcnt(0)
	v_readfirstlane_b32 s0, v1
	v_readlane_b32 s98, v255, 13
	s_add_i32 s0, s0, s98
	s_cmp_ge_i32 s0, s14
	s_cbranch_scc1 .LBB0_117

.LBB0_166:
	s_barrier
	s_and_saveexec_b64 s[0:1], s[12:13]
	s_cbranch_execz .LBB0_170
	s_mov_b64 s[4:5], exec
	v_mbcnt_lo_u32_b32 v1, s4, 0
	v_mbcnt_hi_u32_b32 v1, s5, v1
	v_cmp_eq_u32_e32 vcc, 0, v1
	s_and_saveexec_b64 s[2:3], vcc
	s_cbranch_execz .LBB0_169
	s_bcnt1_i32_b64 s4, s[4:5]
	s_waitcnt vmcnt(0)
	v_mov_b32_e32 v2, s4
	v_readlane_b32 s4, v254, 43
	v_readlane_b32 s5, v254, 44
	s_nop 4
	v_readlane_b32 s4, v254, 20
	s_nop 1
	v_mov_b32_e32 v2, s4

.LBB0_173:
	s_or_b64 exec, exec, s[0:1]
	s_waitcnt lgkmcnt(0)
	s_barrier
	ds_read_b32 v1, v161
	s_waitcnt lgkmcnt(0)
	v_readfirstlane_b32 s20, v1
	v_readlane_b32 s98, v255, 13
	s_add_i32 s20, s20, s98
	s_cmp_ge_i32 s20, s18
	s_cbranch_scc1 .LBB0_287

.LBB0_295:
	s_or_b64 exec, exec, s[2:3]
	s_waitcnt lgkmcnt(0)
	s_barrier
	ds_read_b32 v1, v161
	s_waitcnt lgkmcnt(0)
	v_readfirstlane_b32 s14, v1
	v_readlane_b32 s98, v255, 13
	s_add_i32 s14, s14, s98
	s_cmpk_gt_i32 s14, 0x83f
	s_cbranch_scc1 .LBB0_398

.LBB0_399:
	s_and_b64 vcc, exec, s[0:1]
	s_cbranch_vccz .LBB0_446
	s_cmp_gt_i32 s18, 0
	s_mov_b64 s[0:1], -1
	s_cbranch_scc0 .LBB0_560
	s_cmp_gt_i32 s18, 1
	s_cbranch_scc0 .LBB0_448
	v_lshlrev_b32_e32 v64, 4, v0
	v_readlane_b32 s4, v253, 43
	v_readlane_b32 s5, v253, 44
	v_lshrrev_b32_e32 v65, 4, v0
	v_and_b32_e32 v76, 15, v0
	v_mul_u32_u24_e32 v65, 0x110, v65
	v_lshl_add_u32 v65, v76, 4, v65
	v_add_u32_e32 v65, 0x9800, v65
	s_nop 4
	global_load_dwordx4 v[72:75], v64, s[4:5]
	v_add_u32_e32 v76, 0x1000, v64
	global_load_dwordx4 v[84:87], v76, s[4:5]
	v_add_u32_e32 v76, 0x2000, v64
	global_load_dwordx4 v[88:91], v76, s[4:5]
	v_add_u32_e32 v76, 0x3000, v64
	global_load_dwordx4 v[92:95], v76, s[4:5]
	v_add_u32_e32 v76, 0x4000, v64
	global_load_dwordx4 v[96:99], v76, s[4:5]
	v_add_u32_e32 v76, 0x5000, v64
	global_load_dwordx4 v[100:103], v76, s[4:5]
	v_add_u32_e32 v76, 0x6000, v64
	global_load_dwordx4 v[104:107], v76, s[4:5]
	v_add_u32_e32 v76, 0x7000, v64
	global_load_dwordx4 v[108:111], v76, s[4:5]
	s_waitcnt vmcnt(0)
	ds_write_b128 v65, v[72:75]
	ds_write_b128 v65, v[84:87] offset:4352
	ds_write_b128 v65, v[88:91] offset:8704
	ds_write_b128 v65, v[92:95] offset:13056
	ds_write_b128 v65, v[96:99] offset:17408
	ds_write_b128 v65, v[100:103] offset:21760
	ds_write_b128 v65, v[104:107] offset:26112
	ds_write_b128 v65, v[108:111] offset:30464
	s_waitcnt lgkmcnt(0)
	s_barrier
	s_and_saveexec_b64 s[0:1], s[12:13]
	v_readlane_b32 s14, v254, 52
	v_readlane_b32 s15, v254, 53
	s_cbranch_execz .LBB0_406
	s_mov_b64 s[4:5], exec
	v_mbcnt_lo_u32_b32 v1, s4, 0
	v_mbcnt_hi_u32_b32 v1, s5, v1
	v_cmp_eq_u32_e32 vcc, 0, v1
	s_and_saveexec_b64 s[2:3], vcc
	s_cbranch_execz .LBB0_405
	s_bcnt1_i32_b64 s4, s[4:5]
	s_waitcnt vmcnt(0)
	v_mov_b32_e32 v2, s4
	v_readlane_b32 s4, v254, 43
	v_readlane_b32 s5, v254, 44
	s_nop 4
	v_readlane_b32 s4, v254, 20
	s_nop 1
	v_mov_b32_e32 v2, s4

.LBB0_409:
	s_or_b64 exec, exec, s[0:1]
	s_waitcnt lgkmcnt(0)
	s_barrier
	ds_read_b32 v1, v161
	s_waitcnt lgkmcnt(0)
	v_readfirstlane_b32 s2, v1
	v_readlane_b32 s98, v255, 13
	s_add_i32 s2, s2, s98
	s_cmpk_gt_i32 s2, 0x113f
	s_cbranch_scc1 .LBB0_447

.LBB0_448:
	s_and_b64 vcc, exec, s[0:1]
	s_cbranch_vccz .LBB0_559
	v_lshlrev_b32_e32 v64, 4, v0
	v_readlane_b32 s4, v253, 41
	v_readlane_b32 s5, v253, 42
	v_lshrrev_b32_e32 v65, 3, v0
	v_and_b32_e32 v76, 7, v0
	v_mul_u32_u24_e32 v65, 0x90, v65
	v_lshl_add_u32 v65, v76, 4, v65
	v_add_u32_e32 v65, 0x4000, v65
	s_nop 4
	global_load_dwordx4 v[72:75], v64, s[4:5]
	v_add_u32_e32 v76, 0x1000, v64
	global_load_dwordx4 v[84:87], v76, s[4:5]
	v_add_u32_e32 v76, 0x2000, v64
	global_load_dwordx4 v[88:91], v76, s[4:5]
	v_add_u32_e32 v76, 0x3000, v64
	global_load_dwordx4 v[92:95], v76, s[4:5]
	s_waitcnt vmcnt(0)
	ds_write_b128 v65, v[72:75]
	ds_write_b128 v65, v[84:87] offset:4608
	ds_write_b128 v65, v[88:91] offset:9216
	ds_write_b128 v65, v[92:95] offset:13824
	s_waitcnt lgkmcnt(0)
	s_barrier
	s_and_saveexec_b64 s[0:1], s[12:13]
	s_cbranch_execz .LBB0_453
	s_mov_b64 s[4:5], exec
	v_mbcnt_lo_u32_b32 v1, s4, 0
	v_mbcnt_hi_u32_b32 v1, s5, v1
	v_cmp_eq_u32_e32 vcc, 0, v1
	s_and_saveexec_b64 s[2:3], vcc
	s_cbranch_execz .LBB0_452
	s_bcnt1_i32_b64 s4, s[4:5]
	s_waitcnt vmcnt(0)
	v_mov_b32_e32 v2, s4
	v_readlane_b32 s4, v254, 43
	v_readlane_b32 s5, v254, 44
	s_nop 4
	v_readlane_b32 s4, v254, 20
	s_nop 1
	v_mov_b32_e32 v2, s4

.LBB0_456:
	s_or_b64 exec, exec, s[0:1]
	s_waitcnt lgkmcnt(0)
	s_barrier
	ds_read_b32 v1, v161
	s_waitcnt lgkmcnt(0)
	v_readfirstlane_b32 s21, v1
	v_readlane_b32 s98, v255, 13
	s_add_i32 s21, s21, s98
	s_cmp_ge_i32 s21, s17
	s_cbranch_scc1 .LBB0_559

.LBB0_562:
	s_and_b64 vcc, exec, s[0:1]
	s_cbranch_vccz .LBB0_741
	s_barrier
	s_and_saveexec_b64 s[0:1], s[12:13]
	s_cbranch_execz .LBB0_567
	s_mov_b64 s[4:5], exec
	v_mbcnt_lo_u32_b32 v1, s4, 0
	v_mbcnt_hi_u32_b32 v1, s5, v1
	v_cmp_eq_u32_e32 vcc, 0, v1
	s_and_saveexec_b64 s[2:3], vcc
	s_cbranch_execz .LBB0_566
	s_bcnt1_i32_b64 s4, s[4:5]
	s_waitcnt vmcnt(0)
	v_mov_b32_e32 v2, s4
	v_readlane_b32 s4, v254, 43
	v_readlane_b32 s5, v254, 44
	s_nop 4
	v_readlane_b32 s4, v254, 20
	s_nop 1
	v_mov_b32_e32 v2, s4

.LBB0_570:
	s_or_b64 exec, exec, s[4:5]
	s_waitcnt lgkmcnt(0)
	s_barrier
	ds_read_b32 v1, v161
	v_readlane_b32 s0, v254, 49
	s_waitcnt lgkmcnt(0)
	v_readfirstlane_b32 s18, v1
	v_readlane_b32 s98, v255, 13
	s_add_i32 s18, s18, s98
	s_cmp_ge_i32 s18, s0
	s_cbranch_scc1 .LBB0_740
